# Z + P10 q-projection loop: per-step LDS staging + global loads moved from in front of the step's fragment reads to behind its eighth MFMA
# speedup vs baseline: 1.0045x; 1.0045x over previous
; #define LAS __attribute__((address_space(3)))
; #define MMA16(X, Y, ACC) ACC = __builtin_amdgcn_mfma_f32_16x16x32_bf16((X), (Y), (ACC), 0, 0, 0)
; #define QG_LD(j, step) do { const int ko_ = (step) * 64; ra[j][0] = *(const u32x4*)(ap + ko_); ra[j][1] = *(const u32x4*)(ap + ko_ + 8); ra[j][2] = *(const u32x4*)(bp + ko_); ra[j][3] = *(const u32x4*)(bp + ko_ + 8); } while (0)
; #define QG_ST(j, buf) do { LAS bf16* As_ = (LAS bf16*)(lds + AT_KS + (buf) * 2 * GBUF); LAS bf16* Bs_ = As_ + 128 * GP; \
;         *(LAS u32x4*)(As_ + lr * GP + lc) = ra[j][0]; *(LAS u32x4*)(As_ + lr * GP + lc + 8) = ra[j][1]; *(LAS u32x4*)(Bs_ + lr * GP + lc) = ra[j][2]; *(LAS u32x4*)(Bs_ + lr * GP + lc + 8) = ra[j][3]; } while (0)
;     ...
;         for (int st4 = 0; st4 < 32; st4 += 4) {
; #pragma unroll
;             for (int u = 0; u < 4; ++u) { const int st = st4 + u, cb = u & 1, j = (u + 1) & 3;
;                 if (st + 1 < 32) QG_ST(j, cb ^ 1);
;                 if (st + 5 < 32) QG_LD(j, st + 5);
;                 const LAS bf16* As = (const LAS bf16*)(lds + AT_KS + cb * 2 * GBUF); const LAS bf16* Bs = As + 128 * GP;
;                 bf16x8 af[2], bfr[8][2];
; #pragma unroll
;                 for (int ks = 0; ks < 2; ++ks) af[ks] = *(const LAS bf16x8*)(As + (16 * w + fr) * GP + 32 * ks + 8 * fq);
; #pragma unroll
;                 for (int nb = 0; nb < 8; ++nb)
; #pragma unroll
;                     for (int ks = 0; ks < 2; ++ks) bfr[nb][ks] = *(const LAS bf16x8*)(Bs + (16 * nb + fr) * GP + 32 * ks + 8 * fq);
;                 __builtin_amdgcn_sched_barrier(0);
; #pragma unroll
;                 for (int ks = 0; ks < 2; ++ks)
; #pragma unroll
;                     for (int nb = 0; nb < 8; ++nb) MMA16(bfr[nb][ks], af[ks], acc[nb]);
;                 __builtin_amdgcn_sched_barrier(0);
;                 __syncthreads(); }
.LBB0_46:
	ds_read_b128 v[164:167], v162
	ds_read_b128 v[168:171], v162 offset:64
	ds_read_b128 v[172:175], v163
	ds_read_b128 v[182:185], v163 offset:64
	ds_read_b128 v[188:191], v163 offset:2560
	ds_read_b128 v[196:199], v163 offset:2624
	ds_read_b128 v[200:203], v163 offset:5120
	ds_read_b128 v[204:207], v163 offset:5184
	ds_read_b128 v[208:211], v163 offset:7680
	ds_read_b128 v[212:215], v163 offset:7744
	ds_read_b128 v[216:219], v163 offset:10240
	ds_read_b128 v[220:223], v163 offset:10304
	ds_read_b128 v[224:227], v163 offset:12800
	ds_read_b128 v[228:231], v163 offset:12864
	ds_read_b128 v[232:235], v163 offset:15360
	ds_read_b128 v[236:239], v163 offset:15424
	ds_read_b128 v[240:243], v163 offset:17920
	ds_read_b128 v[244:247], v163 offset:17984
	s_waitcnt lgkmcnt(14)
	v_mfma_f32_16x16x32_bf16 v[100:103], v[172:175], v[164:167], v[100:103]
	s_waitcnt lgkmcnt(13)
	v_mfma_f32_16x16x32_bf16 v[104:107], v[188:191], v[164:167], v[104:107]
	s_waitcnt lgkmcnt(11)
	v_mfma_f32_16x16x32_bf16 v[108:111], v[200:203], v[164:167], v[108:111]
	s_waitcnt lgkmcnt(9)
	v_mfma_f32_16x16x32_bf16 v[112:115], v[208:211], v[164:167], v[112:115]
	s_waitcnt lgkmcnt(7)
	v_mfma_f32_16x16x32_bf16 v[172:175], v[216:219], v[164:167], v[116:119]
	s_waitcnt lgkmcnt(5)
	v_mfma_f32_16x16x32_bf16 v[188:191], v[224:227], v[164:167], v[120:123]
	s_waitcnt lgkmcnt(3)
	v_mfma_f32_16x16x32_bf16 v[200:203], v[232:235], v[164:167], v[124:127]
	s_waitcnt lgkmcnt(1)
	v_mfma_f32_16x16x32_bf16 v[164:167], v[240:243], v[164:167], v[128:131]
	s_cmp_gt_u32 s14, 30
	s_cbranch_scc1 .Lqst4a
	s_waitcnt vmcnt(2)
	ds_write_b128 v150, v[88:91] offset:36864
	ds_write_b128 v150, v[84:87] offset:36880
	s_waitcnt vmcnt(0)
	ds_write_b128 v150, v[96:99] offset:57344
	ds_write_b128 v150, v[92:95] offset:57360

; #define LAS __attribute__((address_space(3)))
; #define MMA16(X, Y, ACC) ACC = __builtin_amdgcn_mfma_f32_16x16x32_bf16((X), (Y), (ACC), 0, 0, 0)
; #define QG_LD(j, step) do { const int ko_ = (step) * 64; ra[j][0] = *(const u32x4*)(ap + ko_); ra[j][1] = *(const u32x4*)(ap + ko_ + 8); ra[j][2] = *(const u32x4*)(bp + ko_); ra[j][3] = *(const u32x4*)(bp + ko_ + 8); } while (0)
; #define QG_ST(j, buf) do { LAS bf16* As_ = (LAS bf16*)(lds + AT_KS + (buf) * 2 * GBUF); LAS bf16* Bs_ = As_ + 128 * GP; \
;         *(LAS u32x4*)(As_ + lr * GP + lc) = ra[j][0]; *(LAS u32x4*)(As_ + lr * GP + lc + 8) = ra[j][1]; *(LAS u32x4*)(Bs_ + lr * GP + lc) = ra[j][2]; *(LAS u32x4*)(Bs_ + lr * GP + lc + 8) = ra[j][3]; } while (0)
;     ...
;         for (int st4 = 0; st4 < 32; st4 += 4) {
; #pragma unroll
;             for (int u = 0; u < 4; ++u) { const int st = st4 + u, cb = u & 1, j = (u + 1) & 3;
;                 if (st + 1 < 32) QG_ST(j, cb ^ 1);
;                 if (st + 5 < 32) QG_LD(j, st + 5);
;                 const LAS bf16* As = (const LAS bf16*)(lds + AT_KS + cb * 2 * GBUF); const LAS bf16* Bs = As + 128 * GP;
;                 bf16x8 af[2], bfr[8][2];
; #pragma unroll
;                 for (int ks = 0; ks < 2; ++ks) af[ks] = *(const LAS bf16x8*)(As + (16 * w + fr) * GP + 32 * ks + 8 * fq);
; #pragma unroll
;                 for (int nb = 0; nb < 8; ++nb)
; #pragma unroll
;                     for (int ks = 0; ks < 2; ++ks) bfr[nb][ks] = *(const LAS bf16x8*)(Bs + (16 * nb + fr) * GP + 32 * ks + 8 * fq);
;                 __builtin_amdgcn_sched_barrier(0);
; #pragma unroll
;                 for (int ks = 0; ks < 2; ++ks)
; #pragma unroll
;                     for (int nb = 0; nb < 8; ++nb) MMA16(bfr[nb][ks], af[ks], acc[nb]);
;                 __builtin_amdgcn_sched_barrier(0);
;                 __syncthreads(); }
.Lqst4b:
	v_mfma_f32_16x16x32_bf16 v[128:131], v[182:185], v[168:171], v[100:103]
	v_mfma_f32_16x16x32_bf16 v[124:127], v[196:199], v[168:171], v[104:107]
	v_mfma_f32_16x16x32_bf16 v[120:123], v[204:207], v[168:171], v[108:111]
	v_mfma_f32_16x16x32_bf16 v[116:119], v[212:215], v[168:171], v[112:115]
	v_mfma_f32_16x16x32_bf16 v[112:115], v[220:223], v[168:171], v[172:175]
	v_mfma_f32_16x16x32_bf16 v[108:111], v[228:231], v[168:171], v[188:191]
	v_mfma_f32_16x16x32_bf16 v[104:107], v[236:239], v[168:171], v[200:203]
	s_waitcnt lgkmcnt(0)
	v_mfma_f32_16x16x32_bf16 v[100:103], v[244:247], v[168:171], v[164:167]
	s_add_i32 s14, s0, 4
	v_lshl_add_u64 v[142:143], v[142:143], 0, s[20:21]
	v_lshl_add_u64 v[144:145], v[144:145], 0, s[20:21]
	s_cmp_gt_u32 s0, 27
	s_mov_b32 s0, s14
	s_barrier
	s_cbranch_scc1 .LBB0_57
.LBB0_47:
.LBB0_49:
	v_add_u32_e32 v164, v132, v141
	ds_read_b128 v[166:169], v159 offset:36864
	ds_read_b128 v[170:173], v159 offset:36928
	ds_read_b128 v[196:199], v164 offset:57344
	ds_read_b128 v[200:203], v164 offset:57408
	ds_read_b128 v[204:207], v164 offset:59904
	ds_read_b128 v[208:211], v164 offset:59968
	ds_read_b128 v[212:215], v164 offset:62464
	ds_read_b128 v[216:219], v164 offset:62528
	ds_read_b128 v[220:223], v164 offset:65024
	ds_read_b128 v[224:227], v164 offset:65088
	ds_read_b128 v[228:231], v160 offset:10240
	ds_read_b128 v[232:235], v160 offset:10304
	ds_read_b128 v[236:239], v160 offset:12800
	ds_read_b128 v[240:243], v160 offset:12864
	ds_read_b128 v[244:247], v160 offset:15360
	ds_read_b128 v[248:251], v160 offset:15424
	ds_read_b128 v[188:191], v160 offset:17920
	ds_read_b128 v[182:185], v160 offset:17984
	s_waitcnt lgkmcnt(14)
	v_mfma_f32_16x16x32_bf16 v[128:131], v[196:199], v[166:169], v[128:131]
	s_waitcnt lgkmcnt(13)
	v_mfma_f32_16x16x32_bf16 v[124:127], v[204:207], v[166:169], v[124:127]
	s_waitcnt lgkmcnt(11)
	v_mfma_f32_16x16x32_bf16 v[120:123], v[212:215], v[166:169], v[120:123]
	s_waitcnt lgkmcnt(9)
	v_mfma_f32_16x16x32_bf16 v[116:119], v[220:223], v[166:169], v[116:119]
	s_waitcnt lgkmcnt(7)
	v_mfma_f32_16x16x32_bf16 v[196:199], v[228:231], v[166:169], v[112:115]
	s_waitcnt lgkmcnt(5)
	v_mfma_f32_16x16x32_bf16 v[204:207], v[236:239], v[166:169], v[108:111]
	s_waitcnt lgkmcnt(3)
	v_mfma_f32_16x16x32_bf16 v[212:215], v[244:247], v[166:169], v[104:107]
	s_waitcnt lgkmcnt(1)
	v_mfma_f32_16x16x32_bf16 v[166:169], v[188:191], v[166:169], v[100:103]
	s_waitcnt vmcnt(2)
	ds_write_b128 v156, v[40:43]
	ds_write_b128 v156, v[36:39] offset:16
	s_waitcnt vmcnt(0)
	ds_write_b128 v158, v[52:55]
	ds_write_b128 v158, v[44:47] offset:16
	s_cmp_lt_u32 s0, 27
	s_cbranch_scc0 .Lqst1
	global_load_dwordx4 v[36:39], v[144:145], off offset:-240
	global_load_dwordx4 v[40:43], v[144:145], off offset:-256
	global_load_dwordx4 v[44:47], v[142:143], off offset:-240
	global_load_dwordx4 v[52:55], v[142:143], off offset:-256
.Lqst1:
	v_mfma_f32_16x16x32_bf16 v[100:103], v[200:203], v[170:173], v[128:131]
	v_mfma_f32_16x16x32_bf16 v[104:107], v[208:211], v[170:173], v[124:127]
	v_mfma_f32_16x16x32_bf16 v[108:111], v[216:219], v[170:173], v[120:123]
	v_mfma_f32_16x16x32_bf16 v[112:115], v[224:227], v[170:173], v[116:119]
	v_mfma_f32_16x16x32_bf16 v[116:119], v[232:235], v[170:173], v[196:199]
	v_mfma_f32_16x16x32_bf16 v[120:123], v[240:243], v[170:173], v[204:207]
	v_mfma_f32_16x16x32_bf16 v[124:127], v[248:251], v[170:173], v[212:215]
	s_waitcnt lgkmcnt(0)
	v_mfma_f32_16x16x32_bf16 v[128:131], v[182:185], v[170:173], v[166:169]
	s_add_i32 s14, s0, 1
	s_cmp_gt_u32 s14, 26
	s_barrier
; #define LAS __attribute__((address_space(3)))
; #define MMA16(X, Y, ACC) ACC = __builtin_amdgcn_mfma_f32_16x16x32_bf16((X), (Y), (ACC), 0, 0, 0)
; #define QG_LD(j, step) do { const int ko_ = (step) * 64; ra[j][0] = *(const u32x4*)(ap + ko_); ra[j][1] = *(const u32x4*)(ap + ko_ + 8); ra[j][2] = *(const u32x4*)(bp + ko_); ra[j][3] = *(const u32x4*)(bp + ko_ + 8); } while (0)
; #define QG_ST(j, buf) do { LAS bf16* As_ = (LAS bf16*)(lds + AT_KS + (buf) * 2 * GBUF); LAS bf16* Bs_ = As_ + 128 * GP; \
;         *(LAS u32x4*)(As_ + lr * GP + lc) = ra[j][0]; *(LAS u32x4*)(As_ + lr * GP + lc + 8) = ra[j][1]; *(LAS u32x4*)(Bs_ + lr * GP + lc) = ra[j][2]; *(LAS u32x4*)(Bs_ + lr * GP + lc + 8) = ra[j][3]; } while (0)
;     ...
;         for (int st4 = 0; st4 < 32; st4 += 4) {
; #pragma unroll
;             for (int u = 0; u < 4; ++u) { const int st = st4 + u, cb = u & 1, j = (u + 1) & 3;
;                 if (st + 1 < 32) QG_ST(j, cb ^ 1);
;                 if (st + 5 < 32) QG_LD(j, st + 5);
;                 const LAS bf16* As = (const LAS bf16*)(lds + AT_KS + cb * 2 * GBUF); const LAS bf16* Bs = As + 128 * GP;
;                 bf16x8 af[2], bfr[8][2];
; #pragma unroll
;                 for (int ks = 0; ks < 2; ++ks) af[ks] = *(const LAS bf16x8*)(As + (16 * w + fr) * GP + 32 * ks + 8 * fq);
; #pragma unroll
;                 for (int nb = 0; nb < 8; ++nb)
; #pragma unroll
;                     for (int ks = 0; ks < 2; ++ks) bfr[nb][ks] = *(const LAS bf16x8*)(Bs + (16 * nb + fr) * GP + 32 * ks + 8 * fq);
;                 __builtin_amdgcn_sched_barrier(0);
; #pragma unroll
;                 for (int ks = 0; ks < 2; ++ks)
; #pragma unroll
;                     for (int nb = 0; nb < 8; ++nb) MMA16(bfr[nb][ks], af[ks], acc[nb]);
;                 __builtin_amdgcn_sched_barrier(0);
;                 __syncthreads(); }
.LBB0_51:
	ds_read_b128 v[166:169], v162
	ds_read_b128 v[170:173], v162 offset:64
	ds_read_b128 v[182:185], v163
	ds_read_b128 v[188:191], v163 offset:64
	ds_read_b128 v[196:199], v163 offset:2560
	ds_read_b128 v[200:203], v163 offset:2624
	ds_read_b128 v[204:207], v163 offset:5120
	ds_read_b128 v[208:211], v163 offset:5184
	ds_read_b128 v[212:215], v163 offset:7680
	ds_read_b128 v[216:219], v163 offset:7744
	ds_read_b128 v[220:223], v163 offset:10240
	ds_read_b128 v[224:227], v163 offset:10304
	ds_read_b128 v[228:231], v163 offset:12800
	ds_read_b128 v[232:235], v163 offset:12864
	ds_read_b128 v[236:239], v163 offset:15360
	ds_read_b128 v[240:243], v163 offset:15424
	ds_read_b128 v[244:247], v163 offset:17920
	ds_read_b128 v[248:251], v163 offset:17984
	s_waitcnt lgkmcnt(14)
	v_mfma_f32_16x16x32_bf16 v[100:103], v[182:185], v[166:169], v[100:103]
	s_waitcnt lgkmcnt(13)
	v_mfma_f32_16x16x32_bf16 v[104:107], v[196:199], v[166:169], v[104:107]
	s_waitcnt lgkmcnt(11)
	v_mfma_f32_16x16x32_bf16 v[108:111], v[204:207], v[166:169], v[108:111]
	s_waitcnt lgkmcnt(9)
	v_mfma_f32_16x16x32_bf16 v[112:115], v[212:215], v[166:169], v[112:115]
	s_waitcnt lgkmcnt(7)
	v_mfma_f32_16x16x32_bf16 v[116:119], v[220:223], v[166:169], v[116:119]
	s_waitcnt lgkmcnt(5)
	v_mfma_f32_16x16x32_bf16 v[120:123], v[228:231], v[166:169], v[120:123]
	s_waitcnt lgkmcnt(3)
	v_mfma_f32_16x16x32_bf16 v[124:127], v[236:239], v[166:169], v[124:127]
	s_waitcnt lgkmcnt(1)
	v_mfma_f32_16x16x32_bf16 v[128:131], v[244:247], v[166:169], v[128:131]
	s_waitcnt vmcnt(10)
	ds_write_b128 v150, v[56:59] offset:36864
	ds_write_b128 v150, v[48:51] offset:36880
	s_waitcnt vmcnt(8)
	ds_write_b128 v150, v[68:71] offset:57344
	ds_write_b128 v150, v[60:63] offset:57360
	s_cmp_gt_u32 s14, 26
	s_cbranch_scc1 .Lqst2
	global_load_dwordx4 v[48:51], v[144:145], off offset:-112
	global_load_dwordx4 v[56:59], v[144:145], off offset:-128
	global_load_dwordx4 v[60:63], v[142:143], off offset:-112
	global_load_dwordx4 v[68:71], v[142:143], off offset:-128
.Lqst2:
	v_mfma_f32_16x16x32_bf16 v[100:103], v[188:191], v[170:173], v[100:103]
	v_mfma_f32_16x16x32_bf16 v[104:107], v[200:203], v[170:173], v[104:107]
	v_mfma_f32_16x16x32_bf16 v[108:111], v[208:211], v[170:173], v[108:111]
	v_mfma_f32_16x16x32_bf16 v[112:115], v[216:219], v[170:173], v[112:115]
	v_mfma_f32_16x16x32_bf16 v[116:119], v[224:227], v[170:173], v[116:119]
	v_mfma_f32_16x16x32_bf16 v[120:123], v[232:235], v[170:173], v[120:123]
	v_mfma_f32_16x16x32_bf16 v[124:127], v[240:243], v[170:173], v[124:127]
	s_waitcnt lgkmcnt(0)
	v_mfma_f32_16x16x32_bf16 v[128:131], v[248:251], v[170:173], v[128:131]
	s_add_i32 s14, s14, 1
	s_cmp_gt_u32 s14, 26
	s_barrier
.LBB0_53:
	ds_read_b128 v[166:169], v159 offset:36864
	ds_read_b128 v[170:173], v159 offset:36928
	ds_read_b128 v[182:185], v164 offset:57344
	ds_read_b128 v[188:191], v164 offset:57408
	ds_read_b128 v[196:199], v164 offset:59904
	ds_read_b128 v[200:203], v164 offset:59968
	ds_read_b128 v[204:207], v164 offset:62464
	ds_read_b128 v[208:211], v164 offset:62528
	ds_read_b128 v[212:215], v164 offset:65024
	ds_read_b128 v[216:219], v164 offset:65088
	ds_read_b128 v[220:223], v160 offset:10240
	ds_read_b128 v[224:227], v160 offset:10304
	ds_read_b128 v[228:231], v160 offset:12800
	ds_read_b128 v[232:235], v160 offset:12864
	ds_read_b128 v[236:239], v160 offset:15360
	ds_read_b128 v[240:243], v160 offset:15424
	ds_read_b128 v[244:247], v160 offset:17920
	ds_read_b128 v[248:251], v160 offset:17984
	s_waitcnt lgkmcnt(14)
	v_mfma_f32_16x16x32_bf16 v[100:103], v[182:185], v[166:169], v[100:103]
	s_waitcnt lgkmcnt(13)
	v_mfma_f32_16x16x32_bf16 v[104:107], v[196:199], v[166:169], v[104:107]
	s_waitcnt lgkmcnt(11)
	v_mfma_f32_16x16x32_bf16 v[108:111], v[204:207], v[166:169], v[108:111]
	s_waitcnt lgkmcnt(9)
	v_mfma_f32_16x16x32_bf16 v[112:115], v[212:215], v[166:169], v[112:115]
	s_waitcnt lgkmcnt(7)
	v_mfma_f32_16x16x32_bf16 v[116:119], v[220:223], v[166:169], v[116:119]
	s_waitcnt lgkmcnt(5)
	v_mfma_f32_16x16x32_bf16 v[120:123], v[228:231], v[166:169], v[120:123]
	s_waitcnt lgkmcnt(3)
	v_mfma_f32_16x16x32_bf16 v[124:127], v[236:239], v[166:169], v[124:127]
	s_waitcnt lgkmcnt(1)
	v_mfma_f32_16x16x32_bf16 v[128:131], v[244:247], v[166:169], v[128:131]
	s_waitcnt vmcnt(6)
	ds_write_b128 v156, v[72:75]
	ds_write_b128 v156, v[64:67] offset:16
	s_waitcnt vmcnt(4)
	ds_write_b128 v158, v[80:83]
	ds_write_b128 v158, v[76:79] offset:16
	s_cmp_gt_u32 s14, 26
	s_cbranch_scc1 .Lqst3
	global_load_dwordx4 v[64:67], v[144:145], off offset:16
	global_load_dwordx4 v[72:75], v[144:145], off
	global_load_dwordx4 v[76:79], v[142:143], off offset:16
	global_load_dwordx4 v[80:83], v[142:143], off
.Lqst3:
	v_mfma_f32_16x16x32_bf16 v[100:103], v[188:191], v[170:173], v[100:103]
	v_mfma_f32_16x16x32_bf16 v[104:107], v[200:203], v[170:173], v[104:107]
	v_mfma_f32_16x16x32_bf16 v[108:111], v[208:211], v[170:173], v[108:111]
	v_mfma_f32_16x16x32_bf16 v[112:115], v[216:219], v[170:173], v[112:115]
	v_mfma_f32_16x16x32_bf16 v[116:119], v[224:227], v[170:173], v[116:119]
	v_mfma_f32_16x16x32_bf16 v[120:123], v[232:235], v[170:173], v[120:123]
	v_mfma_f32_16x16x32_bf16 v[124:127], v[240:243], v[170:173], v[124:127]
	s_waitcnt lgkmcnt(0)
	v_mfma_f32_16x16x32_bf16 v[128:131], v[248:251], v[170:173], v[128:131]
	s_add_i32 s14, s14, 1
	s_cmp_gt_u32 s14, 30
	s_barrier
	s_branch .LBB0_46
